# P0: batched row loads for gate-up and down weight transposes (32 loads issued before first LDS write); plus select-phase dynamic tile tickets and deferred weight wait
# speedup vs baseline: 1.2238x; 1.0062x over previous
.LBB0_46:
	s_andn2_b64 vcc, exec, s[4:5]
	s_cbranch_vccnz .LBB0_80
	s_add_i32 s53, s37, 0xffffea00
	s_cmpk_gt_u32 s53, 0x57f
	s_cselect_b32 s4, 0xfa80, 0
	s_cselect_b32 s5, 0xb00000, 0
	s_add_i32 s4, s4, s37
	s_waitcnt lgkmcnt(0)
	s_add_u32 s38, s14, s5
	s_addc_u32 s39, s15, 0
	s_add_i32 s4, s4, 0xea00
	s_sext_i32_i16 s5, s4
	s_bfe_u32 s5, s5, 0x5001a
	s_add_i32 s54, s4, s5
	s_and_b32 s5, s54, 0xffe0
	s_sub_i32 s4, s4, s5
	s_sext_i32_i16 s4, s4
	s_lshl_b32 s6, s4, 5
	v_or_b32_e32 v2, s6, v1
	v_cmp_lt_i32_e32 vcc, s46, v2
	v_mov_b32_e32 v112, 0
	v_mov_b32_e32 v113, 0
	v_mov_b32_e32 v114, 0
	v_mov_b32_e32 v115, 0
	v_mov_b32_e32 v116, 0
	v_mov_b32_e32 v117, 0
	v_mov_b32_e32 v118, 0
	v_mov_b32_e32 v119, 0
	v_mov_b32_e32 v120, 0
	v_mov_b32_e32 v121, 0
	v_mov_b32_e32 v122, 0
	v_mov_b32_e32 v123, 0
	v_mov_b32_e32 v124, 0
	v_mov_b32_e32 v125, 0
	v_mov_b32_e32 v126, 0
	v_mov_b32_e32 v127, 0
	v_mov_b32_e32 v128, 0
	v_mov_b32_e32 v129, 0
	v_mov_b32_e32 v130, 0
	v_mov_b32_e32 v131, 0
	v_mov_b32_e32 v132, 0
	v_mov_b32_e32 v133, 0
	v_mov_b32_e32 v134, 0
	v_mov_b32_e32 v135, 0
	v_mov_b32_e32 v136, 0
	v_mov_b32_e32 v137, 0
	v_mov_b32_e32 v138, 0
	v_mov_b32_e32 v139, 0
	v_mov_b32_e32 v140, 0
	v_mov_b32_e32 v141, 0
	v_mov_b32_e32 v142, 0
	v_mov_b32_e32 v143, 0
	s_sext_i32_i16 s4, s54
	s_lshl_b32 s4, s4, 1
	v_ashrrev_i32_e32 v3, 31, v2
	s_andn2_b32 s4, s4, 63
	v_lshl_add_u64 v[2:3], v[2:3], 2, s[38:39]
	s_mov_b64 s[24:25], exec
	s_andn2_b64 exec, exec, vcc
	s_cbranch_execz .Lp0_dn_noload
	v_or_b32_e32 v4, s4, v7
	v_or_b32_e32 v18, s4, v23
	v_ashrrev_i32_e32 v5, 31, v4
	v_ashrrev_i32_e32 v19, 31, v18
	v_or_b32_e32 v72, s4, v24
	v_or_b32_e32 v74, s4, v26
	v_lshlrev_b64 v[4:5], 12, v[4:5]
	v_lshlrev_b64 v[18:19], 12, v[18:19]
	v_ashrrev_i32_e32 v73, 31, v72
	v_ashrrev_i32_e32 v75, 31, v74
	v_lshl_add_u64 v[4:5], v[2:3], 0, v[4:5]
	v_lshl_add_u64 v[18:19], v[2:3], 0, v[18:19]
	v_lshlrev_b64 v[72:73], 12, v[72:73]
	v_lshlrev_b64 v[74:75], 12, v[74:75]
	v_lshl_add_u64 v[72:73], v[2:3], 0, v[72:73]
	v_lshl_add_u64 v[74:75], v[2:3], 0, v[74:75]
	global_load_dword v112, v[4:5], off
	s_nop 0
	global_load_dword v113, v[18:19], off
	s_nop 0
	global_load_dword v114, v[72:73], off
	global_load_dword v115, v[74:75], off
	v_or_b32_e32 v4, s4, v27
	v_or_b32_e32 v18, s4, v29
	v_ashrrev_i32_e32 v5, 31, v4
	v_ashrrev_i32_e32 v19, 31, v18
	v_or_b32_e32 v72, s4, v30
	v_or_b32_e32 v74, s4, v32
	v_lshlrev_b64 v[4:5], 12, v[4:5]
	v_lshlrev_b64 v[18:19], 12, v[18:19]
	v_ashrrev_i32_e32 v73, 31, v72
	v_ashrrev_i32_e32 v75, 31, v74
	v_lshl_add_u64 v[4:5], v[2:3], 0, v[4:5]
	v_lshl_add_u64 v[18:19], v[2:3], 0, v[18:19]
	v_lshlrev_b64 v[72:73], 12, v[72:73]
	v_lshlrev_b64 v[74:75], 12, v[74:75]
	v_lshl_add_u64 v[72:73], v[2:3], 0, v[72:73]
	v_lshl_add_u64 v[74:75], v[2:3], 0, v[74:75]
	global_load_dword v116, v[4:5], off
	s_nop 0
	global_load_dword v117, v[18:19], off
	s_nop 0
	global_load_dword v118, v[72:73], off
	global_load_dword v119, v[74:75], off
	v_or_b32_e32 v4, s4, v33
	v_or_b32_e32 v18, s4, v35
	v_ashrrev_i32_e32 v5, 31, v4
	v_ashrrev_i32_e32 v19, 31, v18
	v_or_b32_e32 v72, s4, v36
	v_or_b32_e32 v74, s4, v38
	v_lshlrev_b64 v[4:5], 12, v[4:5]
	v_lshlrev_b64 v[18:19], 12, v[18:19]
	v_ashrrev_i32_e32 v73, 31, v72
	v_ashrrev_i32_e32 v75, 31, v74
	v_lshl_add_u64 v[4:5], v[2:3], 0, v[4:5]
	v_lshl_add_u64 v[18:19], v[2:3], 0, v[18:19]
	v_lshlrev_b64 v[72:73], 12, v[72:73]
	v_lshlrev_b64 v[74:75], 12, v[74:75]
	v_lshl_add_u64 v[72:73], v[2:3], 0, v[72:73]
	v_lshl_add_u64 v[74:75], v[2:3], 0, v[74:75]
	global_load_dword v120, v[4:5], off
	s_nop 0
	global_load_dword v121, v[18:19], off
	s_nop 0
	global_load_dword v122, v[72:73], off
	global_load_dword v123, v[74:75], off
	v_or_b32_e32 v4, s4, v39
	v_or_b32_e32 v18, s4, v41
	v_ashrrev_i32_e32 v5, 31, v4
	v_ashrrev_i32_e32 v19, 31, v18
	v_or_b32_e32 v72, s4, v42
	v_or_b32_e32 v74, s4, v44
	v_lshlrev_b64 v[4:5], 12, v[4:5]
	v_lshlrev_b64 v[18:19], 12, v[18:19]
	v_ashrrev_i32_e32 v73, 31, v72
	v_ashrrev_i32_e32 v75, 31, v74
	v_lshl_add_u64 v[4:5], v[2:3], 0, v[4:5]
	v_lshl_add_u64 v[18:19], v[2:3], 0, v[18:19]
	v_lshlrev_b64 v[72:73], 12, v[72:73]
	v_lshlrev_b64 v[74:75], 12, v[74:75]
	v_lshl_add_u64 v[72:73], v[2:3], 0, v[72:73]
	v_lshl_add_u64 v[74:75], v[2:3], 0, v[74:75]
	global_load_dword v124, v[4:5], off
	s_nop 0
	global_load_dword v125, v[18:19], off
	s_nop 0
	global_load_dword v126, v[72:73], off
	global_load_dword v127, v[74:75], off
	v_or_b32_e32 v4, s4, v45
	v_or_b32_e32 v18, s4, v47
	v_ashrrev_i32_e32 v5, 31, v4
	v_ashrrev_i32_e32 v19, 31, v18
	v_or_b32_e32 v72, s4, v48
	v_or_b32_e32 v74, s4, v50
	v_lshlrev_b64 v[4:5], 12, v[4:5]
	v_lshlrev_b64 v[18:19], 12, v[18:19]
	v_ashrrev_i32_e32 v73, 31, v72
	v_ashrrev_i32_e32 v75, 31, v74
	v_lshl_add_u64 v[4:5], v[2:3], 0, v[4:5]
	v_lshl_add_u64 v[18:19], v[2:3], 0, v[18:19]
	v_lshlrev_b64 v[72:73], 12, v[72:73]
	v_lshlrev_b64 v[74:75], 12, v[74:75]
	v_lshl_add_u64 v[72:73], v[2:3], 0, v[72:73]
	v_lshl_add_u64 v[74:75], v[2:3], 0, v[74:75]
	global_load_dword v128, v[4:5], off
	s_nop 0
	global_load_dword v129, v[18:19], off
	s_nop 0
	global_load_dword v130, v[72:73], off
	global_load_dword v131, v[74:75], off
	v_or_b32_e32 v4, s4, v51
	v_or_b32_e32 v18, s4, v53
	v_ashrrev_i32_e32 v5, 31, v4
	v_ashrrev_i32_e32 v19, 31, v18
	v_or_b32_e32 v72, s4, v54
	v_or_b32_e32 v74, s4, v56
	v_lshlrev_b64 v[4:5], 12, v[4:5]
	v_lshlrev_b64 v[18:19], 12, v[18:19]
	v_ashrrev_i32_e32 v73, 31, v72
	v_ashrrev_i32_e32 v75, 31, v74
	v_lshl_add_u64 v[4:5], v[2:3], 0, v[4:5]
	v_lshl_add_u64 v[18:19], v[2:3], 0, v[18:19]
	v_lshlrev_b64 v[72:73], 12, v[72:73]
	v_lshlrev_b64 v[74:75], 12, v[74:75]
	v_lshl_add_u64 v[72:73], v[2:3], 0, v[72:73]
	v_lshl_add_u64 v[74:75], v[2:3], 0, v[74:75]
	global_load_dword v132, v[4:5], off
	s_nop 0
	global_load_dword v133, v[18:19], off
	s_nop 0
	global_load_dword v134, v[72:73], off
	global_load_dword v135, v[74:75], off
	v_or_b32_e32 v4, s4, v57
	v_or_b32_e32 v18, s4, v59
	v_ashrrev_i32_e32 v5, 31, v4
	v_ashrrev_i32_e32 v19, 31, v18
	v_or_b32_e32 v72, s4, v60
	v_or_b32_e32 v74, s4, v61
	v_lshlrev_b64 v[4:5], 12, v[4:5]
	v_lshlrev_b64 v[18:19], 12, v[18:19]
	v_ashrrev_i32_e32 v73, 31, v72
	v_ashrrev_i32_e32 v75, 31, v74
	v_lshl_add_u64 v[4:5], v[2:3], 0, v[4:5]
	v_lshl_add_u64 v[18:19], v[2:3], 0, v[18:19]
	v_lshlrev_b64 v[72:73], 12, v[72:73]
	v_lshlrev_b64 v[74:75], 12, v[74:75]
	v_lshl_add_u64 v[72:73], v[2:3], 0, v[72:73]
	v_lshl_add_u64 v[74:75], v[2:3], 0, v[74:75]
	global_load_dword v136, v[4:5], off
	s_nop 0
	global_load_dword v137, v[18:19], off
	s_nop 0
	global_load_dword v138, v[72:73], off
	global_load_dword v139, v[74:75], off
	v_or_b32_e32 v18, s4, v62
	v_ashrrev_i32_e32 v19, 31, v18
	v_or_b32_e32 v72, s4, v63
	v_or_b32_e32 v74, s4, v64
	v_or_b32_e32 v76, s4, v65
	v_lshlrev_b64 v[18:19], 12, v[18:19]
	v_ashrrev_i32_e32 v73, 31, v72
	v_ashrrev_i32_e32 v75, 31, v74
	v_ashrrev_i32_e32 v77, 31, v76
	v_lshl_add_u64 v[18:19], v[2:3], 0, v[18:19]
	v_lshlrev_b64 v[72:73], 12, v[72:73]
	v_lshlrev_b64 v[74:75], 12, v[74:75]
	v_lshlrev_b64 v[76:77], 12, v[76:77]
	v_lshl_add_u64 v[72:73], v[2:3], 0, v[72:73]
	v_lshl_add_u64 v[74:75], v[2:3], 0, v[74:75]
	v_lshl_add_u64 v[2:3], v[2:3], 0, v[76:77]
	global_load_dword v140, v[18:19], off
	s_nop 0
	global_load_dword v141, v[72:73], off
	global_load_dword v142, v[74:75], off
	global_load_dword v143, v[2:3], off
.Lp0_dn_noload:
	s_mov_b64 exec, s[24:25]
	s_cmpk_lt_u32 s53, 0x580
	s_cselect_b32 s5, s47, 0x2300000
	s_waitcnt vmcnt(28)
	v_add_u32_e32 v144, v20, v21
	ds_write2_b32 v144, v112, v113 offset1:66
	v_add_u32_e32 v144, v20, v25
	ds_write2_b32 v144, v114, v115 offset1:66
	s_waitcnt vmcnt(24)
	v_add_u32_e32 v144, v20, v28
	ds_write2_b32 v144, v116, v117 offset1:66
	v_add_u32_e32 v144, v20, v31
	ds_write2_b32 v144, v118, v119 offset1:66
	s_waitcnt vmcnt(20)
	v_add_u32_e32 v144, v20, v34
	ds_write2_b32 v144, v120, v121 offset1:66
	v_add_u32_e32 v144, v20, v37
	ds_write2_b32 v144, v122, v123 offset1:66
	s_waitcnt vmcnt(16)
	v_add_u32_e32 v144, v20, v40
	ds_write2_b32 v144, v124, v125 offset1:66
	v_add_u32_e32 v144, v20, v43
	ds_write2_b32 v144, v126, v127 offset1:66
	s_waitcnt vmcnt(12)
	v_add_u32_e32 v144, v20, v46
	ds_write2_b32 v144, v128, v129 offset1:66
	v_add_u32_e32 v144, v20, v49
	ds_write2_b32 v144, v130, v131 offset1:66
	s_waitcnt vmcnt(8)
	v_add_u32_e32 v144, v20, v52
	ds_write2_b32 v144, v132, v133 offset1:66
	v_add_u32_e32 v144, v20, v55
	ds_write2_b32 v144, v134, v135 offset1:66
	s_waitcnt vmcnt(4)
	v_add_u32_e32 v144, v20, v58
	ds_write2_b32 v144, v136, v137 offset1:66
	v_add_u32_e32 v144, v20, v58
	ds_write2_b32 v144, v138, v139 offset0:132 offset1:198
	s_waitcnt vmcnt(0)
	v_add_u32_e32 v144, v20, v58
	v_add_u32_e32 v144, 0x400, v144
	ds_write2_b32 v144, v140, v141 offset0:8 offset1:74
	ds_write2_b32 v144, v142, v143 offset0:140 offset1:206
	s_add_u32 s24, s28, s5
	s_waitcnt lgkmcnt(0)
	s_addc_u32 s25, s29, 0
	s_ashr_i32 s5, s4, 31
	ds_read2_b32 v[2:3], v67 offset1:33
	s_lshl_b64 s[4:5], s[4:5], 1
	s_waitcnt lgkmcnt(0)
	v_cvt_pk_bf16_f32 v2, v2, v3
	ds_read2_b32 v[4:5], v67 offset0:66 offset1:99
	v_or_b32_e32 v18, s6, v66
	s_add_u32 s4, s24, s4
	v_lshlrev_b32_e32 v8, 1, v6
	s_waitcnt lgkmcnt(0)
	v_cvt_pk_bf16_f32 v3, v4, v5
	ds_read2_b32 v[4:5], v67 offset0:132 offset1:165
	v_mul_i32_i24_e32 v18, 0xb00, v18
	s_addc_u32 s5, s25, s5
	v_ashrrev_i32_e32 v19, 31, v18
	s_waitcnt lgkmcnt(0)
	v_cvt_pk_bf16_f32 v4, v4, v5
	ds_read2_b32 v[72:73], v67 offset0:198 offset1:231
	v_lshl_add_u64 v[74:75], s[4:5], 0, v[8:9]
	s_waitcnt lgkmcnt(0)
	v_cvt_pk_bf16_f32 v5, v72, v73
	ds_read2_b32 v[72:73], v67 offset0:8 offset1:41
	v_lshl_add_u64 v[18:19], v[18:19], 1, v[74:75]
	v_or_b32_e32 v8, s6, v68
	global_store_dwordx4 v[18:19], v[2:5], off
	s_waitcnt lgkmcnt(0)
	s_nop 0
	v_cvt_pk_bf16_f32 v2, v72, v73
	ds_read2_b32 v[4:5], v67 offset0:74 offset1:107
	v_mul_i32_i24_e32 v72, 0xb00, v8
	s_waitcnt lgkmcnt(0)
	v_cvt_pk_bf16_f32 v3, v4, v5
	ds_read2_b32 v[4:5], v67 offset0:140 offset1:173
	v_ashrrev_i32_e32 v73, 31, v72
	s_waitcnt lgkmcnt(0)
	v_cvt_pk_bf16_f32 v4, v4, v5
	ds_read2_b32 v[18:19], v67 offset0:206 offset1:239
	s_waitcnt lgkmcnt(0)
	v_cvt_pk_bf16_f32 v5, v18, v19
	v_lshl_add_u64 v[72:73], v[72:73], 1, v[74:75]
	v_or_b32_e32 v8, s6, v69
	ds_read2_b32 v[18:19], v67 offset0:16 offset1:49
	global_store_dwordx4 v[72:73], v[2:5], off
	v_mul_i32_i24_e32 v72, 0xb00, v8
	v_ashrrev_i32_e32 v73, 31, v72
	s_waitcnt lgkmcnt(0)
	v_cvt_pk_bf16_f32 v2, v18, v19
	ds_read2_b32 v[4:5], v67 offset0:82 offset1:115
	s_waitcnt lgkmcnt(0)
	v_cvt_pk_bf16_f32 v3, v4, v5
	ds_read2_b32 v[4:5], v67 offset0:148 offset1:181
	s_waitcnt lgkmcnt(0)
	v_cvt_pk_bf16_f32 v4, v4, v5
	ds_read2_b32 v[18:19], v67 offset0:214 offset1:247
	s_waitcnt lgkmcnt(0)
	v_cvt_pk_bf16_f32 v5, v18, v19
	v_lshl_add_u64 v[72:73], v[72:73], 1, v[74:75]
	ds_read2_b32 v[18:19], v67 offset0:24 offset1:57
	global_store_dwordx4 v[72:73], v[2:5], off
	s_waitcnt lgkmcnt(0)
	s_nop 0
	v_cvt_pk_bf16_f32 v2, v18, v19
	ds_read2_b32 v[4:5], v67 offset0:90 offset1:123
	s_waitcnt lgkmcnt(0)
	v_cvt_pk_bf16_f32 v3, v4, v5
	ds_read2_b32 v[4:5], v67 offset0:156 offset1:189
	s_waitcnt lgkmcnt(0)
	v_cvt_pk_bf16_f32 v4, v4, v5
	v_or_b32_e32 v5, s6, v70
	v_mul_i32_i24_e32 v72, 0xb00, v5
	ds_read2_b32 v[18:19], v67 offset0:222 offset1:255
	v_ashrrev_i32_e32 v73, 31, v72
	s_waitcnt lgkmcnt(0)
	v_cvt_pk_bf16_f32 v5, v18, v19
	v_lshl_add_u64 v[18:19], v[72:73], 1, v[74:75]
	global_store_dwordx4 v[18:19], v[2:5], off
	s_waitcnt lgkmcnt(0)

.LBB0_81:
	s_andn2_b64 vcc, exec, s[4:5]
	s_cbranch_vccnz .LBB0_115
	s_and_b32 s4, s37, 0xffff
	s_mul_hi_u32 s5, s4, 0x2e8ba3
	s_mul_i32 s5, s5, 0xfa80
	s_mul_i32 s4, s4, 0xba2f
	s_bfe_u32 s53, s4, 0x1001a
	s_add_i32 s5, s37, s5
	s_cmp_eq_u32 s53, 0
	s_waitcnt lgkmcnt(0)
	s_cselect_b32 s6, s11, s13
	s_cselect_b32 s24, s10, s12
	s_lshr_b32 s4, s4, 17
	s_and_b32 s4, s4, 0x7c00
	s_mulk_i32 s4, 0x2c00
	s_add_u32 s38, s24, s4
	s_sext_i32_i16 s4, s5
	s_mulk_i32 s4, 0xba3
	s_addc_u32 s39, s6, 0
	s_lshr_b32 s6, s4, 31
	s_ashr_i32 s55, s4, 18
	s_add_i32 s55, s55, s6
	s_mul_i32 s4, s55, 0x58
	s_sub_i32 s4, s5, s4
	s_sext_i32_i16 s54, s4
	s_lshl_b32 s6, s54, 5
	v_or_b32_e32 v2, s6, v1
	v_cmp_lt_i32_e32 vcc, s48, v2
	v_mov_b32_e32 v112, 0
	v_mov_b32_e32 v113, 0
	v_mov_b32_e32 v114, 0
	v_mov_b32_e32 v115, 0
	v_mov_b32_e32 v116, 0
	v_mov_b32_e32 v117, 0
	v_mov_b32_e32 v118, 0
	v_mov_b32_e32 v119, 0
	v_mov_b32_e32 v120, 0
	v_mov_b32_e32 v121, 0
	v_mov_b32_e32 v122, 0
	v_mov_b32_e32 v123, 0
	v_mov_b32_e32 v124, 0
	v_mov_b32_e32 v125, 0
	v_mov_b32_e32 v126, 0
	v_mov_b32_e32 v127, 0
	v_mov_b32_e32 v128, 0
	v_mov_b32_e32 v129, 0
	v_mov_b32_e32 v130, 0
	v_mov_b32_e32 v131, 0
	v_mov_b32_e32 v132, 0
	v_mov_b32_e32 v133, 0
	v_mov_b32_e32 v134, 0
	v_mov_b32_e32 v135, 0
	v_mov_b32_e32 v136, 0
	v_mov_b32_e32 v137, 0
	v_mov_b32_e32 v138, 0
	v_mov_b32_e32 v139, 0
	v_mov_b32_e32 v140, 0
	v_mov_b32_e32 v141, 0
	v_mov_b32_e32 v142, 0
	v_mov_b32_e32 v143, 0
	v_ashrrev_i32_e32 v3, 31, v2
	s_lshl_b32 s4, s55, 6
	v_lshl_add_u64 v[2:3], v[2:3], 2, s[38:39]
	s_mov_b64 s[24:25], exec
	s_andn2_b64 exec, exec, vcc
	s_cbranch_execz .Lp0_gu_noload
	v_or_b32_e32 v8, s4, v23
	v_or_b32_e32 v4, s4, v7
	v_mul_i32_i24_e32 v18, 0xb00, v8
	v_or_b32_e32 v8, s4, v24
	v_mul_i32_i24_e32 v4, 0xb00, v4
	v_mul_i32_i24_e32 v72, 0xb00, v8
	v_or_b32_e32 v8, s4, v26
	v_ashrrev_i32_e32 v5, 31, v4
	v_ashrrev_i32_e32 v19, 31, v18
	v_mul_i32_i24_e32 v74, 0xb00, v8
	v_lshl_add_u64 v[4:5], v[4:5], 2, v[2:3]
	v_lshl_add_u64 v[18:19], v[18:19], 2, v[2:3]
	v_ashrrev_i32_e32 v73, 31, v72
	v_ashrrev_i32_e32 v75, 31, v74
	v_lshl_add_u64 v[72:73], v[72:73], 2, v[2:3]
	v_lshl_add_u64 v[74:75], v[74:75], 2, v[2:3]
	global_load_dword v112, v[4:5], off
	s_nop 0
	global_load_dword v113, v[18:19], off
	s_nop 0
	global_load_dword v114, v[72:73], off
	global_load_dword v115, v[74:75], off
	v_or_b32_e32 v8, s4, v29
	v_or_b32_e32 v4, s4, v27
	v_mul_i32_i24_e32 v18, 0xb00, v8
	v_or_b32_e32 v8, s4, v30
	v_mul_i32_i24_e32 v4, 0xb00, v4
	v_mul_i32_i24_e32 v72, 0xb00, v8
	v_or_b32_e32 v8, s4, v32
	v_ashrrev_i32_e32 v5, 31, v4
	v_ashrrev_i32_e32 v19, 31, v18
	v_mul_i32_i24_e32 v74, 0xb00, v8
	v_lshl_add_u64 v[4:5], v[4:5], 2, v[2:3]
	v_lshl_add_u64 v[18:19], v[18:19], 2, v[2:3]
	v_ashrrev_i32_e32 v73, 31, v72
	v_ashrrev_i32_e32 v75, 31, v74
	v_lshl_add_u64 v[72:73], v[72:73], 2, v[2:3]
	v_lshl_add_u64 v[74:75], v[74:75], 2, v[2:3]
	global_load_dword v116, v[4:5], off
	s_nop 0
	global_load_dword v117, v[18:19], off
	s_nop 0
	global_load_dword v118, v[72:73], off
	global_load_dword v119, v[74:75], off
	v_or_b32_e32 v8, s4, v35
	v_or_b32_e32 v4, s4, v33
	v_mul_i32_i24_e32 v18, 0xb00, v8
	v_or_b32_e32 v8, s4, v36
	v_mul_i32_i24_e32 v4, 0xb00, v4
	v_mul_i32_i24_e32 v72, 0xb00, v8
	v_or_b32_e32 v8, s4, v38
	v_ashrrev_i32_e32 v5, 31, v4
	v_ashrrev_i32_e32 v19, 31, v18
	v_mul_i32_i24_e32 v74, 0xb00, v8
	v_lshl_add_u64 v[4:5], v[4:5], 2, v[2:3]
	v_lshl_add_u64 v[18:19], v[18:19], 2, v[2:3]
	v_ashrrev_i32_e32 v73, 31, v72
	v_ashrrev_i32_e32 v75, 31, v74
	v_lshl_add_u64 v[72:73], v[72:73], 2, v[2:3]
	v_lshl_add_u64 v[74:75], v[74:75], 2, v[2:3]
	global_load_dword v120, v[4:5], off
	s_nop 0
	global_load_dword v121, v[18:19], off
	s_nop 0
	global_load_dword v122, v[72:73], off
	global_load_dword v123, v[74:75], off
	v_or_b32_e32 v8, s4, v41
	v_or_b32_e32 v4, s4, v39
	v_mul_i32_i24_e32 v18, 0xb00, v8
	v_or_b32_e32 v8, s4, v42
	v_mul_i32_i24_e32 v4, 0xb00, v4
	v_mul_i32_i24_e32 v72, 0xb00, v8
	v_or_b32_e32 v8, s4, v44
	v_ashrrev_i32_e32 v5, 31, v4
	v_ashrrev_i32_e32 v19, 31, v18
	v_mul_i32_i24_e32 v74, 0xb00, v8
	v_lshl_add_u64 v[4:5], v[4:5], 2, v[2:3]
	v_lshl_add_u64 v[18:19], v[18:19], 2, v[2:3]
	v_ashrrev_i32_e32 v73, 31, v72
	v_ashrrev_i32_e32 v75, 31, v74
	v_lshl_add_u64 v[72:73], v[72:73], 2, v[2:3]
	v_lshl_add_u64 v[74:75], v[74:75], 2, v[2:3]
	global_load_dword v124, v[4:5], off
	s_nop 0
	global_load_dword v125, v[18:19], off
	s_nop 0
	global_load_dword v126, v[72:73], off
	global_load_dword v127, v[74:75], off
	v_or_b32_e32 v8, s4, v47
	v_or_b32_e32 v4, s4, v45
	v_mul_i32_i24_e32 v18, 0xb00, v8
	v_or_b32_e32 v8, s4, v48
	v_mul_i32_i24_e32 v4, 0xb00, v4
	v_mul_i32_i24_e32 v72, 0xb00, v8
	v_or_b32_e32 v8, s4, v50
	v_ashrrev_i32_e32 v5, 31, v4
	v_ashrrev_i32_e32 v19, 31, v18
	v_mul_i32_i24_e32 v74, 0xb00, v8
	v_lshl_add_u64 v[4:5], v[4:5], 2, v[2:3]
	v_lshl_add_u64 v[18:19], v[18:19], 2, v[2:3]
	v_ashrrev_i32_e32 v73, 31, v72
	v_ashrrev_i32_e32 v75, 31, v74
	v_lshl_add_u64 v[72:73], v[72:73], 2, v[2:3]
	v_lshl_add_u64 v[74:75], v[74:75], 2, v[2:3]
	global_load_dword v128, v[4:5], off
	s_nop 0
	global_load_dword v129, v[18:19], off
	s_nop 0
	global_load_dword v130, v[72:73], off
	global_load_dword v131, v[74:75], off
	v_or_b32_e32 v8, s4, v53
	v_or_b32_e32 v4, s4, v51
	v_mul_i32_i24_e32 v18, 0xb00, v8
	v_or_b32_e32 v8, s4, v54
	v_mul_i32_i24_e32 v4, 0xb00, v4
	v_mul_i32_i24_e32 v72, 0xb00, v8
	v_or_b32_e32 v8, s4, v56
	v_ashrrev_i32_e32 v5, 31, v4
	v_ashrrev_i32_e32 v19, 31, v18
	v_mul_i32_i24_e32 v74, 0xb00, v8
	v_lshl_add_u64 v[4:5], v[4:5], 2, v[2:3]
	v_lshl_add_u64 v[18:19], v[18:19], 2, v[2:3]
	v_ashrrev_i32_e32 v73, 31, v72
	v_ashrrev_i32_e32 v75, 31, v74
	v_lshl_add_u64 v[72:73], v[72:73], 2, v[2:3]
	v_lshl_add_u64 v[74:75], v[74:75], 2, v[2:3]
	global_load_dword v132, v[4:5], off
	s_nop 0
	global_load_dword v133, v[18:19], off
	s_nop 0
	global_load_dword v134, v[72:73], off
	global_load_dword v135, v[74:75], off
	v_or_b32_e32 v8, s4, v59
	v_or_b32_e32 v4, s4, v57
	v_mul_i32_i24_e32 v18, 0xb00, v8
	v_or_b32_e32 v8, s4, v60
	v_mul_i32_i24_e32 v4, 0xb00, v4
	v_mul_i32_i24_e32 v72, 0xb00, v8
	v_or_b32_e32 v8, s4, v61
	v_ashrrev_i32_e32 v5, 31, v4
	v_ashrrev_i32_e32 v19, 31, v18
	v_mul_i32_i24_e32 v74, 0xb00, v8
	v_lshl_add_u64 v[4:5], v[4:5], 2, v[2:3]
	v_lshl_add_u64 v[18:19], v[18:19], 2, v[2:3]
	v_ashrrev_i32_e32 v73, 31, v72
	v_ashrrev_i32_e32 v75, 31, v74
	v_lshl_add_u64 v[72:73], v[72:73], 2, v[2:3]
	v_lshl_add_u64 v[74:75], v[74:75], 2, v[2:3]
	global_load_dword v136, v[4:5], off
	s_nop 0
	global_load_dword v137, v[18:19], off
	s_nop 0
	global_load_dword v138, v[72:73], off
	global_load_dword v139, v[74:75], off
	v_or_b32_e32 v5, s4, v62
	v_mul_i32_i24_e32 v18, 0xb00, v5
	v_or_b32_e32 v5, s4, v63
	v_mul_i32_i24_e32 v72, 0xb00, v5
	v_or_b32_e32 v5, s4, v64
	v_mul_i32_i24_e32 v74, 0xb00, v5
	v_or_b32_e32 v5, s4, v65
	v_ashrrev_i32_e32 v19, 31, v18
	v_mul_i32_i24_e32 v76, 0xb00, v5
	v_lshl_add_u64 v[18:19], v[18:19], 2, v[2:3]
	v_ashrrev_i32_e32 v73, 31, v72
	v_ashrrev_i32_e32 v75, 31, v74
	v_ashrrev_i32_e32 v77, 31, v76
	v_lshl_add_u64 v[72:73], v[72:73], 2, v[2:3]
	v_lshl_add_u64 v[74:75], v[74:75], 2, v[2:3]
	v_lshl_add_u64 v[2:3], v[76:77], 2, v[2:3]
	global_load_dword v140, v[18:19], off
	s_nop 0
	global_load_dword v141, v[72:73], off
	global_load_dword v142, v[74:75], off
	global_load_dword v143, v[2:3], off
.Lp0_gu_noload:
	s_mov_b64 exec, s[24:25]
	s_cmpk_lt_u32 s37, 0xb00
	s_cselect_b32 s5, s49, 0x1200000
	s_add_u32 s24, s28, s5
	s_addc_u32 s25, s29, 0
	s_lshl_b32 s33, s54, 6
	s_waitcnt vmcnt(28)
	v_add_u32_e32 v144, v20, v21
	ds_write2_b32 v144, v112, v113 offset1:66
	v_add_u32_e32 v144, v20, v25
	ds_write2_b32 v144, v114, v115 offset1:66
	s_waitcnt vmcnt(24)
	v_add_u32_e32 v144, v20, v28
	ds_write2_b32 v144, v116, v117 offset1:66
	v_add_u32_e32 v144, v20, v31
	ds_write2_b32 v144, v118, v119 offset1:66
	s_waitcnt vmcnt(20)
	v_add_u32_e32 v144, v20, v34
	ds_write2_b32 v144, v120, v121 offset1:66
	v_add_u32_e32 v144, v20, v37
	ds_write2_b32 v144, v122, v123 offset1:66
	s_waitcnt vmcnt(16)
	v_add_u32_e32 v144, v20, v40
	ds_write2_b32 v144, v124, v125 offset1:66
	v_add_u32_e32 v144, v20, v43
	ds_write2_b32 v144, v126, v127 offset1:66
	s_waitcnt vmcnt(12)
	v_add_u32_e32 v144, v20, v46
	ds_write2_b32 v144, v128, v129 offset1:66
	v_add_u32_e32 v144, v20, v49
	ds_write2_b32 v144, v130, v131 offset1:66
	s_waitcnt vmcnt(8)
	v_add_u32_e32 v144, v20, v52
	ds_write2_b32 v144, v132, v133 offset1:66
	v_add_u32_e32 v144, v20, v55
	ds_write2_b32 v144, v134, v135 offset1:66
	s_waitcnt vmcnt(4)
	v_add_u32_e32 v144, v20, v58
	ds_write2_b32 v144, v136, v137 offset1:66
	v_add_u32_e32 v144, v20, v58
	ds_write2_b32 v144, v138, v139 offset0:132 offset1:198
	s_waitcnt vmcnt(0)
	v_add_u32_e32 v144, v20, v58
	v_add_u32_e32 v144, 0x400, v144
	ds_write2_b32 v144, v140, v141 offset0:8 offset1:74
	ds_write2_b32 v144, v142, v143 offset0:140 offset1:206
	s_lshl_b32 s38, s53, 7
	s_ashr_i32 s5, s4, 31
	s_and_b32 s33, s33, 0xffffff00
	s_waitcnt lgkmcnt(0)
	s_lshl_b64 s[4:5], s[4:5], 1
	s_or_b32 s33, s33, s38
	ds_read2_b32 v[2:3], v67 offset1:33
	s_add_u32 s4, s24, s4
	s_waitcnt lgkmcnt(0)
	v_cvt_pk_bf16_f32 v2, v2, v3
	ds_read2_b32 v[4:5], v67 offset0:66 offset1:99
	s_addc_u32 s5, s25, s5
	v_lshlrev_b32_e32 v8, 1, v6
	s_waitcnt lgkmcnt(0)
	v_cvt_pk_bf16_f32 v3, v4, v5
	ds_read2_b32 v[4:5], v67 offset0:132 offset1:165
	v_lshl_add_u64 v[72:73], s[4:5], 0, v[8:9]
	s_and_b32 s4, s6, 0x60
	s_waitcnt lgkmcnt(0)
	v_cvt_pk_bf16_f32 v4, v4, v5
	ds_read2_b32 v[18:19], v67 offset0:198 offset1:231
	v_or_b32_e32 v8, s4, v66
	s_waitcnt lgkmcnt(0)
	v_cvt_pk_bf16_f32 v5, v18, v19
	v_or_b32_e32 v18, s33, v8
	v_ashrrev_i32_e32 v19, 31, v18
	v_lshlrev_b64 v[18:19], 11, v[18:19]
	v_lshl_add_u64 v[18:19], v[72:73], 0, v[18:19]
	ds_read2_b32 v[74:75], v67 offset0:8 offset1:41
	global_store_dwordx4 v[18:19], v[2:5], off
	s_waitcnt lgkmcnt(0)
	s_nop 0
	v_cvt_pk_bf16_f32 v2, v74, v75
	ds_read2_b32 v[4:5], v67 offset0:74 offset1:107
	s_waitcnt lgkmcnt(0)
	v_cvt_pk_bf16_f32 v3, v4, v5
	ds_read2_b32 v[4:5], v67 offset0:140 offset1:173
	s_waitcnt lgkmcnt(0)
	v_cvt_pk_bf16_f32 v4, v4, v5
	v_or_b32_e32 v5, s4, v68
	v_or_b32_e32 v74, s33, v5
	v_ashrrev_i32_e32 v75, 31, v74
	v_lshlrev_b64 v[74:75], 11, v[74:75]
	ds_read2_b32 v[18:19], v67 offset0:206 offset1:239
	s_waitcnt lgkmcnt(0)
	v_cvt_pk_bf16_f32 v5, v18, v19
	v_lshl_add_u64 v[74:75], v[72:73], 0, v[74:75]
	ds_read2_b32 v[18:19], v67 offset0:16 offset1:49
	global_store_dwordx4 v[74:75], v[2:5], off
	s_waitcnt lgkmcnt(0)
	s_nop 0
	v_cvt_pk_bf16_f32 v2, v18, v19
	ds_read2_b32 v[4:5], v67 offset0:82 offset1:115
	s_waitcnt lgkmcnt(0)
	v_cvt_pk_bf16_f32 v3, v4, v5
	ds_read2_b32 v[4:5], v67 offset0:148 offset1:181
	s_waitcnt lgkmcnt(0)
	v_cvt_pk_bf16_f32 v4, v4, v5
	v_or_b32_e32 v5, s4, v69
	v_or_b32_e32 v74, s33, v5
	v_ashrrev_i32_e32 v75, 31, v74
	v_lshlrev_b64 v[74:75], 11, v[74:75]
	ds_read2_b32 v[18:19], v67 offset0:214 offset1:247
	s_waitcnt lgkmcnt(0)
	v_cvt_pk_bf16_f32 v5, v18, v19
	v_lshl_add_u64 v[74:75], v[72:73], 0, v[74:75]
	ds_read2_b32 v[18:19], v67 offset0:24 offset1:57
	global_store_dwordx4 v[74:75], v[2:5], off
	s_waitcnt lgkmcnt(0)
	s_nop 0
	v_cvt_pk_bf16_f32 v2, v18, v19
	ds_read2_b32 v[4:5], v67 offset0:90 offset1:123
	s_waitcnt lgkmcnt(0)
	v_cvt_pk_bf16_f32 v3, v4, v5
	ds_read2_b32 v[4:5], v67 offset0:156 offset1:189
	s_waitcnt lgkmcnt(0)
	v_cvt_pk_bf16_f32 v4, v4, v5
	v_or_b32_e32 v5, s4, v70
	v_or_b32_e32 v74, s33, v5
	v_ashrrev_i32_e32 v75, 31, v74
	ds_read2_b32 v[18:19], v67 offset0:222 offset1:255
	v_lshlrev_b64 v[74:75], 11, v[74:75]
	s_waitcnt lgkmcnt(0)
	v_cvt_pk_bf16_f32 v5, v18, v19
	v_lshl_add_u64 v[18:19], v[72:73], 0, v[74:75]
	global_store_dwordx4 v[18:19], v[2:5], off
	s_waitcnt lgkmcnt(0)
